# v28 + attention: GQA latent batch 7 and all context items handed out by ticket counter
# speedup vs baseline: 1.0073x; 1.0006x over previous
.LBB0_486:
	v_readlane_b32 s16, v255, 19
	s_add_i32 s16, s16, s2
	s_cmpk_lg_i32 s2, 0x100
	s_cbranch_scc1 .Lattn_dyn_orig
	s_cmpk_lt_i32 s16, 0x700
	s_cbranch_scc1 .LBB0_487
	s_cmpk_lt_i32 s16, 0x800
	s_cbranch_scc1 .Lattn_dyn_skip7
	s_cmpk_lt_i32 s16, 0x900
	s_cbranch_scc1 .Lattn_dyn_ticket
	s_cmpk_lt_i32 s16, 0xa00
	s_cbranch_scc1 .LBB0_487
.Lattn_dyn_ticket:
	v_readlane_b32 s100, v252, 7
	s_cmp_lg_u32 s100, 0
	s_cbranch_scc1 .Lattn_dyn_wait
	v_readlane_b32 s100, v252, 16
	v_readlane_b32 s101, v252, 17
	s_sub_u32 s100, s100, 16
	s_subb_u32 s101, s101, 0
	s_load_dwordx2 s[100:101], s[100:101], 0x0
	s_lshl_b32 s16, s72, 8
	s_add_i32 s16, s16, 0x8000
	s_waitcnt lgkmcnt(0)
	s_add_u32 s100, s100, s16
	s_addc_u32 s101, s101, 0
	s_mov_b64 vcc, exec
	s_mov_b64 exec, 1
	v_mov_b32_e32 v0, 1
	v_mov_b32_e32 v1, 0x23c20
	global_atomic_add v0, v161, v0, s[100:101] sc0
	s_waitcnt vmcnt(0)
	ds_write_b32 v1, v0
	s_waitcnt lgkmcnt(0)
	s_mov_b64 exec, vcc
.Lattn_dyn_wait:
	s_barrier
	v_mov_b32_e32 v1, 0x23c20
	ds_read_b32 v0, v1
	s_waitcnt lgkmcnt(0)
	v_readfirstlane_b32 s16, v0
	s_cmpk_lt_u32 s16, 0x240
	s_cbranch_scc0 .LBB0_659
	s_cmpk_lt_u32 s16, 0x100
	s_cbranch_scc1 .Lattn_dyn_b7
	s_cmpk_lt_u32 s16, 0x140
	s_cbranch_scc1 .Lattn_dyn_diff
	s_addk_i32 s16, 0x8c0
	s_branch .LBB0_487
.Lattn_dyn_diff:
	s_addk_i32 s16, 0xa00
	s_branch .LBB0_487
.Lattn_dyn_b7:
	s_addk_i32 s16, 0x700
	s_branch .LBB0_487
